# s5_scan: E tiles prefetched two pieces ahead (second register set), wait moved to the next piece head
# speedup vs baseline: 1.0029x; 1.0026x over previous
; #define LAS __attribute__((address_space(3)))
; __device__ __forceinline__ int lane_id() { int l; asm volatile("v_mbcnt_lo_u32_b32 %0, -1, 0\n\tv_mbcnt_hi_u32_b32 %0, -1, %0" : "=v"(l)); return l; }
; #define lane lane_id()
; __device__ __forceinline__ void lam_pow(float ar, float ai, float dt, float d, float& pr, float& pi) { const float m = __expf(d * ar * dt); float s, c; sincosf(d * ai * dt, &s, &c); pr = m * c; pi = m * s; }
; __device__ __forceinline__ void zoh_scale(float ar, float ai, float dt, float& sr, float& si) {
;     const float th = ai * dt; float s, c; sincosf(th, &s, &c); const float m = __expf(ar * dt); const float sh = sinf(0.5f * th);
;     const float nr = expm1f(ar * dt) * c - 2.0f * sh * sh, li = m * s; const float den = ar * ar + ai * ai;
;     sr = (nr * ar + li * ai) / den; si = (li * ar - nr * ai) / den;
; __device__ __forceinline__ void s5_scan(const Prm& P, LAS unsigned char* lds, int item, int wave) {
;     const int lane = lane_id(), tid = wave * 64 + lane, nl = tid & 31, ss = tid >> 5, b = item >> 6, g = (item >> 1) & 31, half = item & 1, n = half * 32 + nl;
;     const float dt = __expf(P.in[I_LOGDT][g]); const float ar = P.in[I_ARE][g * 64 + n], ai = P.in[I_AIM][g * 64 + n];
;     float Lr, Li; lam_pow(ar, ai, dt, 16.0f, Lr, Li);
;     float L8r = Lr, L8i = Li;
; #pragma unroll
;     for (int q = 0; q < 3; ++q) { const float a = L8r * L8r - L8i * L8i, c = 2.0f * L8r * L8i; L8r = a; L8i = c; }
;     LAS float* tile = (LAS float*)lds; LAS float* agg = tile + 128 * 64;
;     const float* E = (const float*)(P.ws + WS_E); bf16_t* A5 = (bf16_t*)(P.ws + WS_A5);
;     float car = 0.f, cai = 0.f;
;     for (int piece = 0; piece < 4; ++piece) {
;         const size_t rowbase = (size_t)g * 2048 + b * 512 + piece * 128;
; #pragma unroll
;         for (int i = 0; i < 4; ++i) { const int idx = tid + i * 512, r = idx >> 4, part = (idx >> 3) & 1, c4 = idx & 7;
;             *(LAS f32x4*)(tile + r * 64 + part * 32 + c4 * 4) = *(const f32x4*)(E + (rowbase + r) * 128 + part * 64 + half * 32 + c4 * 4); }
.LBB0_815:
	s_andn2_saveexec_b64 s[4:5], s[10:11]
	v_mul_f32_e64 v0, |v2|, s50
	v_rndne_f32_e32 v9, v0
	v_cvt_i32_f32_e32 v8, v9
	v_fma_f32 v0, v9, s51, |v2|
	v_fmac_f32_e32 v0, 0xb3a22168, v9
	v_fmac_f32_e32 v0, 0xa7c234c4, v9
	s_or_b64 exec, exec, s[4:5]
	s_waitcnt vmcnt(0)
	v_mul_f32_e32 v5, 0x41800000, v5
	v_mul_f32_e32 v5, v7, v5
	v_mul_f32_e32 v7, v0, v0
	v_fmamk_f32 v9, v7, 0xb94c1982, v24
	v_fmaak_f32 v9, v7, v9, 0xbe2aaa9d
	v_mul_f32_e32 v9, v7, v9
	v_fmac_f32_e32 v0, v0, v9
	v_fmamk_f32 v9, v7, 0x37d75334, v25
	v_fmaak_f32 v9, v7, v9, 0x3d2aabf7
	v_fmaak_f32 v9, v7, v9, 0xbf000004
	v_fma_f32 v7, v7, v9, 1.0
	v_lshlrev_b32_e32 v9, 30, v8
	v_and_b32_e32 v8, 1, v8
	v_mul_f32_e32 v5, 0x3fb8aa3b, v5
	v_cmp_eq_u32_e32 vcc, 0, v8
	s_lshr_b32 s4, s60, 1
	v_exp_f32_e32 v5, v5
	v_cndmask_b32_e32 v8, v7, v0, vcc
	v_xor_b32_e32 v4, v4, v2
	v_xor_b32_e32 v0, 0x80000000, v0
	s_and_b32 s4, s4, 31
	v_and_b32_e32 v10, 0x80000000, v9
	v_xor_b32_e32 v4, v4, v8
	v_cndmask_b32_e32 v0, v0, v7, vcc
	s_lshl_b32 s36, s4, 11
	v_readlane_b32 s4, v255, 9
	v_xor_b32_e32 v4, v4, v10
	v_bitop3_b32 v0, v0, v9, s52 bitop3:0x78
	v_cmp_class_f32_e64 vcc, v2, s53
	v_add_u32_e32 v21, s4, v6
	v_bfe_u32 v50, v6, 3, 1
	v_cndmask_b32_e32 v0, v28, v0, vcc
	v_cndmask_b32_e32 v2, v28, v4, vcc
	v_lshlrev_b32_e32 v6, 4, v6
	v_mul_f32_e32 v0, v5, v0
	v_mul_f32_e32 v29, v5, v2
	v_and_b32_e32 v51, 0x70, v6
	v_add_u32_e32 v6, 0x200, v21
	v_ashrrev_i32_e32 v16, 4, v6
	v_add_u32_e32 v6, 0x400, v21
	v_fmamk_f32 v32, v29, 0x80000000, v0
	v_ashrrev_i32_e32 v18, 4, v6
	v_add_u32_e32 v6, 0x600, v21
	v_fma_f32 v33, 0, v0, v29
	v_mul_f32_e32 v35, v29, v32
	v_ashrrev_i32_e32 v48, 4, v6
	v_mul_f32_e32 v6, v29, v33
	v_fmac_f32_e32 v35, v0, v33
	v_add_f32_e32 v4, v0, v0
	v_fma_f32 v34, v0, v32, -v6
	v_mul_f32_e32 v37, v0, v35
	v_mul_f32_e32 v2, v29, v29
	v_mul_f32_e32 v5, v29, v4
	v_mul_f32_e32 v6, v29, v35
	v_fmac_f32_e32 v37, v29, v34
	v_fma_f32 v2, v0, v0, -v2
	v_mul_f32_e32 v4, v5, v5
	v_fma_f32 v36, v0, v34, -v6
	v_mul_f32_e32 v39, v0, v37
	v_fma_f32 v4, v2, v2, -v4
	v_mul_f32_e32 v6, v29, v37
	v_fmac_f32_e32 v39, v29, v36
	v_add_f32_e32 v9, v2, v2
	v_mov_b32_e32 v8, v4
	v_fma_f32 v38, v0, v36, -v6
	v_mul_f32_e32 v41, v0, v39
	s_and_b32 s37, s3, 0xfffffe00
	s_bfe_u32 s63, s2, 0x10005
	v_pk_mul_f32 v[8:9], v[4:5], v[8:9]
	v_mul_f32_e32 v6, v29, v39
	v_fmac_f32_e32 v41, v29, v38
	s_ashr_i32 s62, s37, 31
	s_lshl_b32 s64, s63, 7
	v_pk_mov_b32 v[4:5], v[8:9], v[4:5] op_sel:[1,0]
	v_mov_b32_e32 v2, v9
	v_fma_f32 v40, v0, v38, -v6
	v_mul_f32_e32 v43, v0, v41
	v_ashrrev_i32_e32 v23, 5, v21
	v_pk_mul_f32 v[10:11], v[4:5], v[2:3]
	v_ashrrev_i32_e32 v14, 4, v21
	v_mul_f32_e32 v6, v29, v41
	v_fmac_f32_e32 v43, v29, v40
	s_add_u32 s36, s36, s37
	v_pk_fma_f32 v[12:13], v[4:5], v[2:3], v[8:9] neg_lo:[1,0,0] neg_hi:[1,0,0]
	v_pk_mul_f32 v[10:11], v[8:9], v[10:11]
	v_lshlrev_b32_e32 v46, 3, v23
	v_ashrrev_i32_e32 v15, 31, v14
	v_ashrrev_i32_e32 v17, 31, v16
	v_ashrrev_i32_e32 v19, 31, v18
	v_ashrrev_i32_e32 v49, 31, v48
	v_fma_f32 v42, v0, v40, -v6
	v_mul_f32_e32 v6, v29, v43
	s_addc_u32 s37, 0, s62
	v_mov_b32_e32 v4, v12
	v_mov_b32_e32 v5, v11
	v_ashrrev_i32_e32 v47, 31, v46
	v_lshlrev_b32_e32 v54, 8, v14
	v_lshlrev_b32_e32 v55, 8, v16
	v_lshlrev_b32_e32 v56, 8, v18
	v_fma_f32 v44, v0, v42, -v6
	v_mov_b32_e32 v6, v12
	v_mov_b32_e32 v7, v12
	v_mov_b32_e32 v8, v11
	v_mov_b32_e32 v9, v11
	v_pk_mov_b32 v[10:11], v[10:11], v[12:13] op_sel:[1,0]
	v_lshl_add_u64 v[12:13], s[36:37], 0, v[14:15]
	v_lshl_add_u64 v[14:15], s[36:37], 0, v[16:17]
	v_lshl_add_u64 v[16:17], s[36:37], 0, v[18:19]
	v_lshl_add_u64 v[18:19], s[36:37], 0, v[48:49]
	v_lshlrev_b32_e32 v2, 7, v50
	v_cmp_gt_u32_e64 s[4:5], 32, v21
	v_lshlrev_b64 v[12:13], 9, v[12:13]
	v_lshlrev_b32_e32 v21, 8, v50
	v_lshlrev_b64 v[14:15], 9, v[14:15]
	v_lshlrev_b64 v[16:17], 9, v[16:17]
	v_lshlrev_b64 v[18:19], 9, v[18:19]
	v_lshl_add_u64 v[46:47], s[36:37], 0, v[46:47]
	v_add3_u32 v52, 0, v2, v51
	v_lshl_add_u32 v2, v20, 2, 0
	v_lshlrev_b32_e32 v57, 8, v48
	v_or_b32_e32 v12, v12, v21
	v_or_b32_e32 v14, v14, v21
	v_or_b32_e32 v16, v16, v21
	v_or_b32_e32 v18, v18, v21
	v_mad_u64_u32 v[48:49], s[36:37], v46, s54, 0
	v_lshl_add_u32 v53, v23, 8, v2
	v_lshlrev_b32_e32 v58, 11, v23
	v_mov_b32_e32 v22, 0
	v_mul_f32_e32 v30, 0, v29
	v_mul_f32_e32 v45, v0, v43
	v_or3_b32 v12, v12, s64, v51
	v_or3_b32 v14, v14, s64, v51
	v_or3_b32 v16, v16, s64, v51
	v_or3_b32 v18, v18, s64, v51
	v_lshlrev_b32_e32 v20, 1, v20
	s_lshl_b32 s36, s63, 6
	s_mov_b32 s61, 4
	v_cmp_eq_u32_e32 vcc, 15, v23
	v_fma_f32 v31, v0, 0, -v30
	v_fmac_f32_e32 v30, 0, v0
	v_cmp_eq_u32_e64 s[6:7], 1, v23
	v_cmp_eq_u32_e64 s[8:9], 2, v23
	v_cmp_eq_u32_e64 s[10:11], 3, v23
	v_cmp_eq_u32_e64 s[12:13], 4, v23
	v_cmp_eq_u32_e64 s[14:15], 5, v23
	v_cmp_eq_u32_e64 s[16:17], 6, v23
	v_cmp_eq_u32_e64 s[18:19], 7, v23
	v_cmp_eq_u32_e64 s[20:21], 8, v23
	v_cmp_eq_u32_e64 s[22:23], 9, v23
	v_cmp_eq_u32_e64 s[24:25], 10, v23
	v_cmp_eq_u32_e64 s[26:27], 11, v23
	v_cmp_eq_u32_e64 s[28:29], 12, v23
	v_cmp_eq_u32_e64 s[30:31], 13, v23
	v_cmp_eq_u32_e64 s[34:35], 14, v23
	v_fmac_f32_e32 v45, v29, v42
	v_lshl_add_u64 v[12:13], v[12:13], 0, s[38:39]
	v_lshl_add_u64 v[14:15], v[14:15], 0, s[38:39]
	v_lshl_add_u64 v[16:17], v[16:17], 0, s[38:39]
	v_lshl_add_u64 v[18:19], v[18:19], 0, s[38:39]
	v_mad_i32_i24 v21, v47, s54, v49
	v_or3_b32 v20, s36, v20, v48
	v_add_u32_e32 v46, v52, v54
	v_add_u32_e32 v47, v52, v55
	v_add_u32_e32 v48, v52, v56
	v_add_u32_e32 v49, v52, v57
	v_add_u32_e32 v50, v2, v58
	v_add_u32_e32 v51, 0x8000, v53
	v_mov_b32_e32 v23, v22
	v_lshl_add_u64 v[52:53], s[92:93], 0, v[12:13]
	global_load_dwordx4 v[224:227], v[52:53], off
	v_lshl_add_u64 v[52:53], s[92:93], 0, v[14:15]
	global_load_dwordx4 v[228:231], v[52:53], off
	v_lshl_add_u64 v[52:53], s[92:93], 0, v[16:17]
	global_load_dwordx4 v[232:235], v[52:53], off
	v_lshl_add_u64 v[52:53], s[92:93], 0, v[18:19]
	global_load_dwordx4 v[236:239], v[52:53], off
	v_lshl_add_u64 v[12:13], v[12:13], 0, s[44:45]
	v_lshl_add_u64 v[14:15], v[14:15], 0, s[44:45]
	v_lshl_add_u64 v[16:17], v[16:17], 0, s[44:45]
	v_lshl_add_u64 v[18:19], v[18:19], 0, s[44:45]
	v_lshl_add_u64 v[52:53], s[92:93], 0, v[12:13]
	global_load_dwordx4 v[100:103], v[52:53], off
	v_lshl_add_u64 v[52:53], s[92:93], 0, v[14:15]
	global_load_dwordx4 v[104:107], v[52:53], off
	v_lshl_add_u64 v[52:53], s[92:93], 0, v[16:17]
	global_load_dwordx4 v[108:111], v[52:53], off
	v_lshl_add_u64 v[52:53], s[92:93], 0, v[18:19]
	global_load_dwordx4 v[112:115], v[52:53], off
	v_lshl_add_u64 v[12:13], v[12:13], 0, s[44:45]
	v_lshl_add_u64 v[14:15], v[14:15], 0, s[44:45]
	v_lshl_add_u64 v[16:17], v[16:17], 0, s[44:45]
	v_lshl_add_u64 v[18:19], v[18:19], 0, s[44:45]
	s_waitcnt vmcnt(0)
; #define LAS __attribute__((address_space(3)))
; __device__ __forceinline__ void s5_scan(const Prm& P, LAS unsigned char* lds, int item, int wave) {
;     ...
;     for (int piece = 0; piece < 4; ++piece) {
;         const size_t rowbase = (size_t)g * 2048 + b * 512 + piece * 128;
; #pragma unroll
;         for (int i = 0; i < 4; ++i) { const int idx = tid + i * 512, r = idx >> 4, part = (idx >> 3) & 1, c4 = idx & 7;
;             *(LAS f32x4*)(tile + r * 64 + part * 32 + c4 * 4) = *(const f32x4*)(E + (rowbase + r) * 128 + part * 64 + half * 32 + c4 * 4); }
;         __syncthreads();
;         const int r0 = ss * 8; float xr[8], xi[8]; float pr = 0.f, pi = 0.f;
; #pragma unroll
;         for (int j = 0; j < 8; ++j) { xr[j] = pr; xi[j] = pi; const float er = tile[(r0 + j) * 64 + nl], ei = tile[(r0 + j) * 64 + 32 + nl];
;             const float a = Lr * pr - Li * pi + er, c = Lr * pi + Li * pr + ei; pr = a; pi = c; }
;         agg[ss * 64 + nl] = pr; agg[ss * 64 + 32 + nl] = pi;
.LBB0_818:
	v_add_u32_e32 v68, 0x400, v50
	v_add_u32_e32 v72, 0x8000, v2
	v_cndmask_b32_e64 v69, 0, v23, s[4:5]
	v_add_u32_e32 v76, 0x8400, v2
	v_add_u32_e32 v80, 0x8c00, v2
	s_add_i32 s61, s61, -1
	s_cmp_lg_u32 s61, 0
	ds_write_b128 v46, v[224:227]
	ds_write_b128 v47, v[228:231]
	ds_write_b128 v48, v[232:235]
	ds_write_b128 v49, v[236:239]
	s_waitcnt vmcnt(16)
	v_mov_b64_e32 v[224:225], v[100:101]
	v_mov_b64_e32 v[226:227], v[102:103]
	v_mov_b64_e32 v[228:229], v[104:105]
	v_mov_b64_e32 v[230:231], v[106:107]
	v_mov_b64_e32 v[232:233], v[108:109]
	v_mov_b64_e32 v[234:235], v[110:111]
	v_mov_b64_e32 v[236:237], v[112:113]
	v_mov_b64_e32 v[238:239], v[114:115]
	v_lshl_add_u64 v[52:53], s[92:93], 0, v[12:13]
	global_load_dwordx4 v[100:103], v[52:53], off
	v_lshl_add_u64 v[52:53], s[92:93], 0, v[14:15]
	global_load_dwordx4 v[104:107], v[52:53], off
	v_lshl_add_u64 v[52:53], s[92:93], 0, v[16:17]
	global_load_dwordx4 v[108:111], v[52:53], off
	v_lshl_add_u64 v[52:53], s[92:93], 0, v[18:19]
	global_load_dwordx4 v[112:115], v[52:53], off
	v_lshl_add_u64 v[12:13], v[12:13], 0, s[44:45]
	v_lshl_add_u64 v[14:15], v[14:15], 0, s[44:45]
	v_lshl_add_u64 v[16:17], v[16:17], 0, s[44:45]
	v_lshl_add_u64 v[18:19], v[18:19], 0, s[44:45]
	s_waitcnt lgkmcnt(0)
	s_barrier
	ds_read2_b32 v[148:149], v50 offset1:32
	ds_read2_b32 v[150:151], v50 offset0:64 offset1:96
	ds_read2_b32 v[152:153], v50 offset0:128 offset1:160
	ds_read2_b32 v[154:155], v50 offset0:192 offset1:224
	ds_read2_b32 v[156:157], v68 offset1:32
	ds_read2_b32 v[158:159], v68 offset0:64 offset1:96
	ds_read2_b32 v[160:161], v68 offset0:128 offset1:160
	ds_read2_b32 v[162:163], v68 offset0:192 offset1:224
	s_waitcnt lgkmcnt(7)
	v_add_f32_e32 v59, v31, v148
	v_add_f32_e32 v57, v30, v149
	v_mul_f32_e32 v54, v29, v57
	v_fma_f32 v54, v0, v59, -v54
	s_waitcnt lgkmcnt(6)
	v_add_f32_e32 v58, v150, v54
	v_mul_f32_e32 v52, v0, v57
	v_fmac_f32_e32 v52, v29, v59
	v_add_f32_e32 v55, v151, v52
	v_mul_f32_e32 v54, v29, v55
	v_fma_f32 v54, v0, v58, -v54
	s_waitcnt lgkmcnt(5)
	v_add_f32_e32 v56, v152, v54
	v_mul_f32_e32 v52, v29, v58
	v_fmac_f32_e32 v52, v0, v55
	v_add_f32_e32 v53, v153, v52
	v_mul_f32_e32 v52, v29, v53
	v_fma_f32 v52, v0, v56, -v52
	s_waitcnt lgkmcnt(4)
	v_add_f32_e32 v54, v154, v52
	v_mul_f32_e32 v52, v29, v56
	v_fmac_f32_e32 v52, v0, v53
	v_add_f32_e32 v52, v155, v52
	v_mul_f32_e32 v62, v29, v52
	v_fma_f32 v62, v0, v54, -v62
	s_waitcnt lgkmcnt(3)
	v_add_f32_e32 v65, v156, v62
	v_mul_f32_e32 v60, v29, v54
	v_fmac_f32_e32 v60, v0, v52
	v_add_f32_e32 v63, v157, v60
	v_mul_f32_e32 v62, v29, v63
	v_fma_f32 v62, v0, v65, -v62
	s_waitcnt lgkmcnt(2)
	v_add_f32_e32 v64, v158, v62
	v_mul_f32_e32 v60, v29, v65
	v_fmac_f32_e32 v60, v0, v63
	v_add_f32_e32 v61, v159, v60
	v_mul_f32_e32 v60, v29, v61
	v_fma_f32 v60, v0, v64, -v60
	s_waitcnt lgkmcnt(1)
	v_add_f32_e32 v62, v160, v60
	v_mul_f32_e32 v60, v29, v64
	v_fmac_f32_e32 v60, v0, v61
	v_add_f32_e32 v60, v161, v60
	v_mul_f32_e32 v68, v29, v60
	v_fma_f32 v68, v0, v62, -v68
	s_waitcnt lgkmcnt(0)
	v_add_f32_e32 v66, v162, v68
	v_mul_f32_e32 v68, v29, v62
	v_fmac_f32_e32 v68, v0, v60
	v_add_f32_e32 v67, v163, v68
	ds_write2_b32 v51, v66, v67 offset1:32
	v_pk_mul_f32 v[66:67], v[4:5], v[22:23]
	s_waitcnt lgkmcnt(0)
	s_barrier
	v_sub_f32_e32 v70, v66, v67
	ds_read2_b32 v[66:67], v72 offset1:32
	v_cndmask_b32_e64 v68, 0, v22, s[4:5]
	v_pk_mul_f32 v[22:23], v[10:11], v[22:23]
	s_waitcnt lgkmcnt(0)
	v_add_f32_e32 v66, v70, v66
	v_add_f32_e32 v22, v22, v23
	v_add_f32_e32 v22, v22, v67
	v_cndmask_b32_e64 v74, v68, v66, s[6:7]
	v_cndmask_b32_e64 v75, v69, v22, s[6:7]
	ds_read2_b32 v[68:69], v72 offset0:64 offset1:96
	v_pk_mul_f32 v[22:23], v[10:11], v[22:23] op_sel_hi:[1,0]
	s_nop 0
	v_pk_fma_f32 v[70:71], v[4:5], v[66:67], v[22:23] neg_lo:[0,0,1] neg_hi:[0,0,1]
	v_pk_fma_f32 v[22:23], v[4:5], v[66:67], v[22:23] op_sel_hi:[1,0,1]
	s_nop 0
	v_mov_b32_e32 v71, v23
	ds_read2_b32 v[22:23], v72 offset0:128 offset1:160
	ds_read2_b32 v[66:67], v72 offset0:192 offset1:224
	s_waitcnt lgkmcnt(2)
	v_pk_add_f32 v[68:69], v[68:69], v[70:71]
	ds_read2_b32 v[72:73], v76 offset1:32
	v_pk_mul_f32 v[70:71], v[8:9], v[68:69]
	v_cndmask_b32_e64 v77, v74, v68, s[8:9]
	v_cndmask_b32_e64 v78, v75, v69, s[8:9]
	v_pk_fma_f32 v[74:75], v[6:7], v[68:69], v[70:71] op_sel:[0,0,1] op_sel_hi:[1,1,0] neg_lo:[0,0,1] neg_hi:[0,0,1]
	v_pk_fma_f32 v[68:69], v[6:7], v[68:69], v[70:71] op_sel:[0,0,1] op_sel_hi:[1,1,0]
	s_nop 0
	v_mov_b32_e32 v75, v69
	s_waitcnt lgkmcnt(2)
	v_pk_add_f32 v[22:23], v[22:23], v[74:75]
	s_nop 0
	v_pk_mul_f32 v[68:69], v[8:9], v[22:23]
	v_cndmask_b32_e64 v74, v77, v22, s[10:11]
	v_cndmask_b32_e64 v75, v78, v23, s[10:11]
	v_pk_fma_f32 v[70:71], v[6:7], v[22:23], v[68:69] op_sel:[0,0,1] op_sel_hi:[1,1,0] neg_lo:[0,0,1] neg_hi:[0,0,1]
	v_pk_fma_f32 v[22:23], v[6:7], v[22:23], v[68:69] op_sel:[0,0,1] op_sel_hi:[1,1,0]
	s_nop 0
	v_mov_b32_e32 v71, v23
	s_waitcnt lgkmcnt(1)
	v_pk_add_f32 v[22:23], v[66:67], v[70:71]
	s_nop 0
	v_pk_mul_f32 v[66:67], v[8:9], v[22:23]
	v_cndmask_b32_e64 v70, v74, v22, s[12:13]
	v_cndmask_b32_e64 v71, v75, v23, s[12:13]
	v_pk_fma_f32 v[68:69], v[6:7], v[22:23], v[66:67] op_sel:[0,0,1] op_sel_hi:[1,1,0] neg_lo:[0,0,1] neg_hi:[0,0,1]
	v_pk_fma_f32 v[22:23], v[6:7], v[22:23], v[66:67] op_sel:[0,0,1] op_sel_hi:[1,1,0]
	s_nop 0
	v_mov_b32_e32 v69, v23
	s_waitcnt lgkmcnt(0)
	v_pk_add_f32 v[22:23], v[72:73], v[68:69]
	ds_read2_b32 v[68:69], v76 offset0:64 offset1:96
	v_cndmask_b32_e64 v77, v70, v22, s[14:15]
	v_mul_f32_e32 v66, v5, v23
	v_mul_f32_e32 v70, v10, v22
	v_cndmask_b32_e64 v78, v71, v23, s[14:15]
	v_pk_fma_f32 v[66:67], v[4:5], v[22:23], v[66:67] op_sel_hi:[1,1,0] neg_lo:[0,0,1] neg_hi:[0,0,1]
	v_pk_fma_f32 v[22:23], v[10:11], v[22:23], v[70:71] op_sel_hi:[1,1,0]
	ds_read2_b32 v[70:71], v76 offset0:128 offset1:160
	ds_read2_b32 v[72:73], v76 offset0:192 offset1:224
	v_mov_b32_e32 v67, v23
	s_waitcnt lgkmcnt(2)
; __device__ __forceinline__ void s5_scan(const Prm& P, LAS unsigned char* lds, int item, int wave) {
;     ...
;         float cr = car, ci = cai, mr = 0.f, mi = 0.f;
; #pragma unroll
;         for (int s2 = 0; s2 < 16; ++s2) { if (s2 == ss) { mr = cr; mi = ci; } const float a = L8r * cr - L8i * ci + agg[s2 * 64 + nl], c = L8r * ci + L8i * cr + agg[s2 * 64 + 32 + nl]; cr = a; ci = c; }
;         car = cr; cai = ci;
	v_pk_add_f32 v[22:23], v[68:69], v[66:67]
	v_add_u32_e32 v76, 0x8800, v2
	v_pk_mul_f32 v[66:67], v[8:9], v[22:23]
	v_cndmask_b32_e64 v77, v77, v22, s[16:17]
	v_cndmask_b32_e64 v78, v78, v23, s[16:17]
	v_pk_fma_f32 v[68:69], v[6:7], v[22:23], v[66:67] op_sel:[0,0,1] op_sel_hi:[1,1,0] neg_lo:[0,0,1] neg_hi:[0,0,1]
	v_pk_fma_f32 v[22:23], v[6:7], v[22:23], v[66:67] op_sel:[0,0,1] op_sel_hi:[1,1,0]
	ds_read2_b32 v[74:75], v76 offset1:32
	v_mov_b32_e32 v69, v23
	s_waitcnt lgkmcnt(2)
	v_pk_add_f32 v[22:23], v[70:71], v[68:69]
	s_nop 0
	v_pk_mul_f32 v[66:67], v[8:9], v[22:23]
	v_cndmask_b32_e64 v70, v77, v22, s[18:19]
	v_cndmask_b32_e64 v71, v78, v23, s[18:19]
	v_pk_fma_f32 v[68:69], v[6:7], v[22:23], v[66:67] op_sel:[0,0,1] op_sel_hi:[1,1,0] neg_lo:[0,0,1] neg_hi:[0,0,1]
	v_pk_fma_f32 v[22:23], v[6:7], v[22:23], v[66:67] op_sel:[0,0,1] op_sel_hi:[1,1,0]
	s_nop 0
	v_mov_b32_e32 v69, v23
	s_waitcnt lgkmcnt(1)
	v_pk_add_f32 v[22:23], v[72:73], v[68:69]
	s_nop 0
	v_pk_mul_f32 v[66:67], v[8:9], v[22:23]
	v_cndmask_b32_e64 v70, v70, v22, s[20:21]
	v_cndmask_b32_e64 v71, v71, v23, s[20:21]
	v_pk_fma_f32 v[68:69], v[6:7], v[22:23], v[66:67] op_sel:[0,0,1] op_sel_hi:[1,1,0] neg_lo:[0,0,1] neg_hi:[0,0,1]
	v_pk_fma_f32 v[22:23], v[6:7], v[22:23], v[66:67] op_sel:[0,0,1] op_sel_hi:[1,1,0]
	s_nop 0
	v_mov_b32_e32 v69, v23
	s_waitcnt lgkmcnt(0)
	v_pk_add_f32 v[22:23], v[74:75], v[68:69]
	s_nop 0
	v_cndmask_b32_e64 v78, v70, v22, s[22:23]
	v_cndmask_b32_e64 v79, v71, v23, s[22:23]
	ds_read2_b32 v[66:67], v76 offset0:64 offset1:96
	ds_read2_b32 v[68:69], v76 offset0:128 offset1:160
	ds_read2_b32 v[70:71], v76 offset0:192 offset1:224
	v_pk_mul_f32 v[74:75], v[8:9], v[22:23]
	ds_read2_b32 v[72:73], v80 offset1:32
	v_pk_fma_f32 v[76:77], v[6:7], v[22:23], v[74:75] op_sel:[0,0,1] op_sel_hi:[1,1,0] neg_lo:[0,0,1] neg_hi:[0,0,1]
	v_pk_fma_f32 v[22:23], v[6:7], v[22:23], v[74:75] op_sel:[0,0,1] op_sel_hi:[1,1,0]
	s_nop 0
	v_mov_b32_e32 v77, v23
	s_waitcnt lgkmcnt(3)
	v_pk_add_f32 v[22:23], v[66:67], v[76:77]
	s_nop 0
	v_pk_mul_f32 v[66:67], v[8:9], v[22:23]
	v_cndmask_b32_e64 v76, v78, v22, s[24:25]
	v_cndmask_b32_e64 v77, v79, v23, s[24:25]
	v_pk_fma_f32 v[74:75], v[6:7], v[22:23], v[66:67] op_sel:[0,0,1] op_sel_hi:[1,1,0] neg_lo:[0,0,1] neg_hi:[0,0,1]
	v_pk_fma_f32 v[22:23], v[6:7], v[22:23], v[66:67] op_sel:[0,0,1] op_sel_hi:[1,1,0]
	s_nop 0
	v_mov_b32_e32 v75, v23
	s_waitcnt lgkmcnt(2)
	v_pk_add_f32 v[22:23], v[68:69], v[74:75]
	s_nop 0
	v_pk_mul_f32 v[66:67], v[8:9], v[22:23]
	v_cndmask_b32_e64 v74, v76, v22, s[26:27]
	v_cndmask_b32_e64 v75, v77, v23, s[26:27]
	v_pk_fma_f32 v[68:69], v[6:7], v[22:23], v[66:67] op_sel:[0,0,1] op_sel_hi:[1,1,0] neg_lo:[0,0,1] neg_hi:[0,0,1]
	v_pk_fma_f32 v[22:23], v[6:7], v[22:23], v[66:67] op_sel:[0,0,1] op_sel_hi:[1,1,0]
	s_nop 0
	v_mov_b32_e32 v69, v23
	s_waitcnt lgkmcnt(1)
	v_pk_add_f32 v[22:23], v[70:71], v[68:69]
	s_nop 0
	v_pk_mul_f32 v[66:67], v[8:9], v[22:23]
	v_cndmask_b32_e64 v76, v74, v22, s[28:29]
	v_cndmask_b32_e64 v77, v75, v23, s[28:29]
	v_pk_fma_f32 v[68:69], v[6:7], v[22:23], v[66:67] op_sel:[0,0,1] op_sel_hi:[1,1,0] neg_lo:[0,0,1] neg_hi:[0,0,1]
	v_pk_fma_f32 v[22:23], v[6:7], v[22:23], v[66:67] op_sel:[0,0,1] op_sel_hi:[1,1,0]
	v_lshl_add_u64 v[74:75], s[92:93], 0, v[20:21]
	v_mov_b32_e32 v69, v23
	s_waitcnt lgkmcnt(0)
	v_pk_add_f32 v[68:69], v[72:73], v[68:69]
	ds_read2_b32 v[22:23], v80 offset0:64 offset1:96
	ds_read2_b32 v[66:67], v80 offset0:128 offset1:160
	ds_read2_b32 v[70:71], v80 offset0:192 offset1:224
	v_pk_mul_f32 v[72:73], v[8:9], v[68:69]
	v_cndmask_b32_e64 v78, v76, v68, s[30:31]
	v_cndmask_b32_e64 v79, v77, v69, s[30:31]
	v_pk_fma_f32 v[76:77], v[6:7], v[68:69], v[72:73] op_sel:[0,0,1] op_sel_hi:[1,1,0] neg_lo:[0,0,1] neg_hi:[0,0,1]
	v_pk_fma_f32 v[68:69], v[6:7], v[68:69], v[72:73] op_sel:[0,0,1] op_sel_hi:[1,1,0]
	v_lshl_add_u64 v[20:21], v[20:21], 0, s[46:47]
	v_mov_b32_e32 v77, v69
	s_waitcnt lgkmcnt(2)
	v_pk_add_f32 v[22:23], v[22:23], v[76:77]
	s_nop 0
	v_pk_mul_f32 v[68:69], v[8:9], v[22:23]
	v_cndmask_b32_e64 v76, v78, v22, s[34:35]
	v_cndmask_b32_e64 v77, v79, v23, s[34:35]
	v_pk_fma_f32 v[72:73], v[6:7], v[22:23], v[68:69] op_sel:[0,0,1] op_sel_hi:[1,1,0] neg_lo:[0,0,1] neg_hi:[0,0,1]
	v_pk_fma_f32 v[22:23], v[6:7], v[22:23], v[68:69] op_sel:[0,0,1] op_sel_hi:[1,1,0]
	s_nop 0
	v_mov_b32_e32 v73, v23
	s_waitcnt lgkmcnt(1)
; __device__ __forceinline__ unsigned f2bf(float f) { unsigned u = __builtin_bit_cast(unsigned, f); return (u + 0x7fffu + ((u >> 16) & 1u)) >> 16; }
; __device__ __forceinline__ void s5_scan(const Prm& P, LAS unsigned char* lds, int item, int wave) {
;     ...
;         float pwr = 1.f, pwi = 0.f;
; #pragma unroll
;         for (int j = 0; j < 8; ++j) { const float hr = xr[j] + pwr * mr - pwi * mi, hi = xi[j] + pwr * mi + pwi * mr;
;             bf16_t* dst = A5 + (rowbase + r0 + j) * 384 + 256 + n; dst[0] = (bf16_t)f2bf(hr); dst[64] = (bf16_t)f2bf(hi);
;             const float a = pwr * Lr - pwi * Li, c = pwr * Li + pwi * Lr; pwr = a; pwi = c; }
;         __syncthreads();
;     }
	v_pk_add_f32 v[22:23], v[66:67], v[72:73]
	s_nop 0
	v_pk_mul_f32 v[66:67], v[8:9], v[22:23]
	v_cndmask_b32_e32 v72, v76, v22, vcc
	v_cndmask_b32_e32 v73, v77, v23, vcc
	v_pk_fma_f32 v[68:69], v[6:7], v[22:23], v[66:67] op_sel:[0,0,1] op_sel_hi:[1,1,0] neg_lo:[0,0,1] neg_hi:[0,0,1]
	v_pk_fma_f32 v[22:23], v[6:7], v[22:23], v[66:67] op_sel:[0,0,1] op_sel_hi:[1,1,0]
	v_add_f32_e32 v66, 0, v73
	v_add_f32_e32 v22, 0, v72
	v_fmac_f32_e32 v22, 0x80000000, v73
	v_mov_b32_e32 v69, v23
	v_bfe_u32 v23, v22, 16, 1
	v_add3_u32 v67, v22, v23, s55
	v_add_co_u32_e64 v22, s[36:37], s58, v74
	v_fmac_f32_e32 v66, 0, v72
	s_nop 0
	v_addc_co_u32_e64 v23, s[36:37], 0, v75, s[36:37]
	global_store_short_d16_hi v[22:23], v67, off offset:512
	v_bfe_u32 v67, v66, 16, 1
	v_fmac_f32_e32 v59, v32, v72
	v_add3_u32 v66, v66, v67, s55
	v_fma_f32 v59, -v33, v73, v59
	global_store_short_d16_hi v[22:23], v66, off offset:640
	v_fmac_f32_e32 v57, v32, v73
	v_bfe_u32 v66, v59, 16, 1
	v_fmac_f32_e32 v57, v33, v72
	v_add3_u32 v59, v59, v66, s55
	global_store_short_d16_hi v[22:23], v59, off offset:1280
	v_bfe_u32 v59, v57, 16, 1
	v_add3_u32 v57, v57, v59, s55
	v_fmac_f32_e32 v58, v34, v72
	global_store_short_d16_hi v[22:23], v57, off offset:1408
	v_fma_f32 v57, -v35, v73, v58
	v_fmac_f32_e32 v55, v34, v73
	v_bfe_u32 v58, v57, 16, 1
	v_fmac_f32_e32 v55, v35, v72
	v_add3_u32 v57, v57, v58, s55
	global_store_short_d16_hi v[22:23], v57, off offset:2048
	v_bfe_u32 v57, v55, 16, 1
	v_add3_u32 v55, v55, v57, s55
	v_fmac_f32_e32 v56, v36, v72
	global_store_short_d16_hi v[22:23], v55, off offset:2176
	v_fma_f32 v55, -v37, v73, v56
	v_fmac_f32_e32 v53, v36, v73
	v_bfe_u32 v56, v55, 16, 1
	v_fmac_f32_e32 v53, v37, v72
	v_add3_u32 v55, v55, v56, s55
	global_store_short_d16_hi v[22:23], v55, off offset:2816
	v_bfe_u32 v55, v53, 16, 1
	v_add3_u32 v53, v53, v55, s55
	v_fmac_f32_e32 v54, v38, v72
	global_store_short_d16_hi v[22:23], v53, off offset:2944
	v_fma_f32 v53, -v39, v73, v54
	v_fmac_f32_e32 v52, v38, v73
	v_bfe_u32 v54, v53, 16, 1
	v_fmac_f32_e32 v52, v39, v72
	v_add3_u32 v53, v53, v54, s55
	global_store_short_d16_hi v[22:23], v53, off offset:3584
	v_bfe_u32 v53, v52, 16, 1
	v_add3_u32 v52, v52, v53, s55
	v_fmac_f32_e32 v65, v40, v72
	global_store_short_d16_hi v[22:23], v52, off offset:3712
	v_fma_f32 v22, -v41, v73, v65
	v_bfe_u32 v23, v22, 16, 1
	v_fmac_f32_e32 v63, v40, v73
	v_add3_u32 v52, v22, v23, s55
	v_add_co_u32_e64 v22, s[36:37], s59, v74
	v_fmac_f32_e32 v63, v41, v72
	s_nop 0
	v_addc_co_u32_e64 v23, s[36:37], 0, v75, s[36:37]
	global_store_short_d16_hi v[22:23], v52, off offset:256
	v_bfe_u32 v52, v63, 16, 1
	v_add3_u32 v52, v63, v52, s55
	v_fmac_f32_e32 v64, v42, v72
	global_store_short_d16_hi v[22:23], v52, off offset:384
	v_fma_f32 v52, -v43, v73, v64
	v_fmac_f32_e32 v61, v42, v73
	v_bfe_u32 v53, v52, 16, 1
	v_fmac_f32_e32 v61, v43, v72
	v_add3_u32 v52, v52, v53, s55
	global_store_short_d16_hi v[22:23], v52, off offset:1024
	v_bfe_u32 v52, v61, 16, 1
	v_add3_u32 v52, v61, v52, s55
	v_fmac_f32_e32 v62, v44, v72
	global_store_short_d16_hi v[22:23], v52, off offset:1152
	v_fma_f32 v52, -v45, v73, v62
	v_fmac_f32_e32 v60, v44, v73
	v_bfe_u32 v53, v52, 16, 1
	v_fmac_f32_e32 v60, v45, v72
	v_add3_u32 v52, v52, v53, s55
	global_store_short_d16_hi v[22:23], v52, off offset:1792
	v_bfe_u32 v52, v60, 16, 1
	v_add3_u32 v52, v60, v52, s55
	global_store_short_d16_hi v[22:23], v52, off offset:1920
	s_waitcnt lgkmcnt(0)
	v_pk_add_f32 v[22:23], v[70:71], v[68:69]
	s_barrier
	s_cbranch_scc1 .LBB0_818
	v_readlane_b32 s4, v255, 1
	s_add_i32 s60, s60, s4
	s_add_i32 s3, s3, s94
	s_add_i32 s2, s2, s33
	s_cmpk_gt_i32 s60, 0xff
	v_readlane_b32 s5, v255, 2
	s_cbranch_scc0 .LBB0_813
; #define LAS __attribute__((address_space(3)))
; __device__ __forceinline__ int lane_id() { int l; asm volatile("v_mbcnt_lo_u32_b32 %0, -1, 0\n\tv_mbcnt_hi_u32_b32 %0, -1, %0" : "=v"(l)); return l; }
; #define lane lane_id()
; template <bool FULL, bool STORE = true>
; __device__ __forceinline__ void hg_item(const Prm& P, LAS unsigned char* lds, int item, int wave) {
;     unsigned char* ws = P.ws; const int lane = lane_id(), tid = wave * 64 + lane;
;     const int b = item >> 6, h = (item >> 3) & 7, seg = item & 7;
;     const int l31 = lane & 31, lh = lane >> 5;
;     const int k2 = lane * 2, tg = wave;
;     const int kb = wave >> 1, vb0 = (wave & 1) * 2;
;     const _Float16* LF = (const _Float16*)P.out; const bf16_t* Q = (const bf16_t*)(ws + WS_Q); const bf16_t* IV = (const bf16_t*)(ws + WS_IV); const bf16_t* GH = (const bf16_t*)(ws + WS_GH);
;     bf16_t* AHG = (bf16_t*)(ws + WS_AHG);
;     float* AGG = (float*)(ws + WS_HGAGG); float* DEC = (float*)(ws + WS_HGDEC);
	v_writelane_b32 v255, s76, 20
	s_lshl_b32 s2, s97, 1
	s_add_u32 s62, s92, 0xf400000
	v_writelane_b32 v255, s77, 21
	v_writelane_b32 v255, s94, 22
	s_addc_u32 s63, s93, 0
	s_mov_b32 s75, 0
	v_writelane_b32 v255, s95, 23
	v_writelane_b32 v255, s90, 24
	s_mov_b32 s81, s75
	v_mbcnt_lo_u32_b32 v0, -1, 0
	v_writelane_b32 v255, s91, 25
	v_writelane_b32 v255, s2, 26
	s_lshr_b32 s2, s80, 7
	s_add_u32 s64, s92, 0x7400000
	s_addc_u32 s65, s93, 0
	s_add_u32 s66, s92, 0x13400000
	s_addc_u32 s67, s93, 0
	s_add_u32 s4, s92, 0x1c400000
	s_addc_u32 s5, s93, 0
	v_writelane_b32 v255, s4, 27
	s_lshl_b32 s3, s2, 5
	s_lshl_b32 s2, s2, 6
	v_writelane_b32 v255, s5, 28
	s_add_i32 s2, s2, 0
	v_writelane_b32 v255, s3, 29
	s_add_i32 s2, s2, 0x15c00
	v_writelane_b32 v255, s2, 30
	s_and_b32 s2, s80, 64
	v_writelane_b32 v255, s2, 31
	s_lshl_b32 s2, s97, 9
	s_add_i32 s60, s2, 0
	s_lshl_b32 s2, s97, 4
	s_add_i32 s61, s2, 0
	s_lshl_b32 s55, s97, 3
	s_add_i32 s60, s60, 0x20800
	s_add_i32 s58, s61, 0x11400
	s_cmpk_lt_u32 s80, 0xc0
	s_cselect_b64 s[76:77], -1, 0
	s_bfe_u32 s2, s80, 0x20006
	s_cmpk_gt_u32 s80, 0xff
	s_cselect_b64 s[4:5], -1, 0
	s_and_b32 s18, s80, 0xffffff80
	s_lshl_b32 s3, s2, 5
	s_lshl_b32 s2, s2, 7
	s_add_i32 s96, s18, 0
	s_and_b32 s59, s55, 0x1fffffe0
	v_writelane_b32 v255, s3, 32
	s_add_i32 s2, s2, 0
	s_add_i32 s96, s96, 0x21800
	v_writelane_b32 v255, s2, 33
	s_and_b64 s[2:3], s[88:89], exec
	s_mov_b32 s2, s97
	s_cselect_b32 s97, 0, 32
	s_cmp_eq_u32 s2, 2
	s_cselect_b32 s3, 32, 0
	s_cmpk_gt_u32 s80, 0x7f
	s_cselect_b64 s[6:7], -1, 0
	s_cmpk_gt_u32 s80, 0xbf
	s_cselect_b64 s[8:9], -1, 0
	s_cmpk_gt_u32 s80, 0x13f
	s_cselect_b64 s[10:11], -1, 0
	s_cmpk_gt_u32 s80, 0x17f
	s_cselect_b64 s[12:13], -1, 0
	s_cmpk_gt_u32 s80, 0x1bf
	v_writelane_b32 v255, s3, 34
	s_cselect_b64 s[14:15], -1, 0
	s_cmpk_gt_u32 s80, 0x1ff
	s_cselect_b64 s[16:17], -1, 0
	v_writelane_b32 v255, s2, 35
	s_or_b32 s3, s97, 1
	v_writelane_b32 v255, s3, 36
	s_or_b32 s3, s97, 2
	v_writelane_b32 v255, s3, 37
	s_or_b32 s3, s97, 3
	v_writelane_b32 v255, s3, 38
	s_or_b32 s3, s97, 8
	v_writelane_b32 v255, s3, 39
	s_or_b32 s3, s97, 9
	v_writelane_b32 v255, s3, 40
	s_or_b32 s3, s97, 10
	v_writelane_b32 v255, s3, 41
	s_or_b32 s3, s97, 11
	v_writelane_b32 v255, s3, 42
	s_or_b32 s3, s97, 16
	v_writelane_b32 v255, s3, 43
	s_or_b32 s3, s97, 17
	v_writelane_b32 v255, s3, 44
	s_or_b32 s3, s97, 18
	v_writelane_b32 v255, s3, 45
	s_or_b32 s3, s97, 19
	v_writelane_b32 v255, s3, 46
	s_or_b32 s3, s97, 24
	v_writelane_b32 v255, s3, 47
	s_or_b32 s3, s97, 25
	v_writelane_b32 v255, s3, 48
	s_or_b32 s3, s97, 26
	s_mulk_i32 s2, 0x880
	v_writelane_b32 v255, s3, 49
	s_or_b32 s3, s97, 27
	v_writelane_b32 v255, s3, 50
	s_add_i32 s2, s2, 0
	v_writelane_b32 v255, s2, 51
	s_add_u32 s2, s92, s18
	s_addc_u32 s3, s93, 0
	s_add_u32 s2, s2, 0x1f500040
	v_writelane_b32 v255, s2, 52
	s_addc_u32 s2, s3, 0
	v_writelane_b32 v255, s2, 53
	v_mov_b32_e32 v75, 0
	v_readlane_b32 s2, v255, 7
	v_readlane_b32 s3, v255, 8
	s_mov_b32 s20, s2
	s_lshl_b32 s54, s2, 4
	v_readlane_b32 s2, v255, 1
	s_lshl_b32 s2, s2, 4
	v_readlane_b32 s3, v255, 2
	v_writelane_b32 v255, s2, 54
	s_add_u32 s2, s55, 64
	v_writelane_b32 v255, s2, 55
	s_mov_b32 s2, s80
	v_writelane_b32 v255, s2, 56
	s_addc_u32 s90, 0, 0
	v_mbcnt_hi_u32_b32 v108, -1, v0
	v_writelane_b32 v255, s3, 57
	s_lshl_b64 s[2:3], s[80:81], 8
	s_and_b32 s2, s2, 0xffffc000
	s_add_u32 s18, s70, s2
	s_addc_u32 s19, s71, s3
	s_add_u32 s78, s18, 0x20000
	s_addc_u32 s79, s19, 0
	s_add_u32 s80, s92, s2
	s_addc_u32 s81, s93, s3
	s_movk_i32 s3, 0x110
	v_mov_b32_e32 v109, 0x358637bd
	s_movk_i32 s72, 0x90
	s_add_i32 s73, 0, 0x1e400
	s_movk_i32 s95, 0x7fff
	s_mov_b32 s2, s20
	s_mov_b32 s91, s20
	s_movk_i32 s94, 0x210
	s_branch .LBB0_822
